# K-loop back-edge rotation variant: SALU block at the end of the last (lighter) load segment before its waits and barrier
# baseline (speedup 1.0000x reference)
; #define PG8_STAGE(bufoff, gbase, voff) do { _Pragma("unroll") for (int _i = 0; _i < 2; ++_i) \
;         __builtin_amdgcn_global_load_lds((const unsigned*)((const char*)(gbase) + (voff)[_i]), (PG8_LAS unsigned*)(lds + (bufoff) + ldsw + _i * 8192), 16, 0, 0); } while (0)
; #define PG8_LDA(dst, b, h) do { _Pragma("unroll") for (int m = 0; m < 4; ++m) _Pragma("unroll") for (int k = 0; k < 2; ++k) dst[m][k] = *(const PG8_LAS bf16x8*)(lds + PG8_SA(b, h) + aoff + m * 2048 + k * 1024); } while (0)
; #define PG8_LDB(dst, b, h) do { _Pragma("unroll") for (int n = 0; n < 2; ++n) _Pragma("unroll") for (int k = 0; k < 2; ++k) dst[n][k] = *(const PG8_LAS bf16x8*)(lds + PG8_SB(b, h) + boff + n * 2048 + k * 1024); } while (0)
; #define PG8_MMA(ai, bj, At, Bt) do { __builtin_amdgcn_s_setprio(1); _Pragma("unroll") for (int m = 0; m < 4; ++m) _Pragma("unroll") for (int n = 0; n < 2; ++n) _Pragma("unroll") for (int k = 0; k < 2; ++k) \
;         acc[ai][bj][m][n] = __builtin_amdgcn_mfma_f32_16x16x32_bf16(Bt[n][k], At[m][k], acc[ai][bj][m][n], 0, 0, 0); __builtin_amdgcn_s_setprio(0); } while (0)
; #define PG8_WAIT_V(n) asm volatile("s_waitcnt vmcnt(" #n ")" ::: "memory")
; #define PG8_WAIT_L(n) asm volatile("s_waitcnt lgkmcnt(" #n ")" ::: "memory")
; #define PG8_BAR __builtin_amdgcn_s_barrier()
; #define PG8_SCHED __builtin_amdgcn_sched_barrier(0)
; template <class Epi, class Sched, bool ALIGN_EPI = false, bool SP2 = false>
; __device__ __forceinline__ void gemm_phase(PG8_LAS unsigned char* lds, const Gemm g, const Sched& S, const Epi& E, const int tid_in) {
;     ...
;             PG8_LDB(B0, 0, 0); PG8_LDB(B1, 0, 1); PG8_SCHED; PG8_LDA(At, 0, 0); PG8_STAGE(PG8_SA(1, 1), a1 + hstepA, voffA);
;             PG8_WAIT_V(8); PG8_WAIT_L(0); PG8_BAR; PG8_MMA(0, 0, At, B0); PG8_MMA(0, 1, At, B1); PG8_BAR; PG8_SCHED;
;             PG8_LDA(At, 0, 1); PG8_STAGE(PG8_SB(0, 0), b2, voffB); PG8_STAGE(PG8_SB(0, 1), b2 + hstep, voffB); PG8_STAGE(PG8_SA(0, 0), a2, voffA);
.LBB0_226:
	v_add_u32_e32 v142, s26, v252
	v_add_u32_e32 v158, s51, v252
	ds_read_b128 v[130:133], v142
	ds_read_b128 v[134:137], v142 offset:1024
	ds_read_b128 v[138:141], v142 offset:2048
	ds_read_b128 v[142:145], v142 offset:3072
	ds_read_b128 v[146:149], v158
	ds_read_b128 v[150:153], v158 offset:1024
	ds_read_b128 v[154:157], v158 offset:2048
	ds_read_b128 v[158:161], v158 offset:3072
	v_lshl_add_u64 v[194:195], s[46:47], 0, v[222:223]
	s_add_i32 m0, s17, 0xc000
	ds_read_b128 v[162:165], v244
	ds_read_b128 v[166:169], v244 offset:1024
	ds_read_b128 v[170:173], v244 offset:2048
	ds_read_b128 v[174:177], v244 offset:3072
	ds_read_b128 v[178:181], v244 offset:4096
	ds_read_b128 v[182:185], v244 offset:5120
	ds_read_b128 v[186:189], v244 offset:6144
	ds_read_b128 v[190:193], v244 offset:7168
	global_load_lds_dwordx4 v[194:195], off
	v_lshl_add_u64 v[194:195], s[46:47], 0, v[220:221]
	s_add_i32 m0, s17, 0xe000
	s_nop 0
	global_load_lds_dwordx4 v[194:195], off
	s_waitcnt vmcnt(8)
	s_waitcnt lgkmcnt(0)
	s_barrier
	s_setprio 1
	s_waitcnt lgkmcnt(0)
	v_mfma_f32_16x16x32_bf16 v[126:129], v[130:133], v[162:165], v[126:129]
	v_mfma_f32_16x16x32_bf16 v[122:125], v[138:141], v[162:165], v[122:125]
	v_mfma_f32_16x16x32_bf16 v[110:113], v[130:133], v[170:173], v[110:113]
	v_mfma_f32_16x16x32_bf16 v[106:109], v[138:141], v[170:173], v[106:109]
	v_mfma_f32_16x16x32_bf16 v[94:97], v[130:133], v[178:181], v[94:97]
	v_mfma_f32_16x16x32_bf16 v[90:93], v[138:141], v[178:181], v[90:93]
	v_mfma_f32_16x16x32_bf16 v[78:81], v[130:133], v[186:189], v[78:81]
	v_mfma_f32_16x16x32_bf16 v[74:77], v[138:141], v[186:189], v[74:77]
	v_mfma_f32_16x16x32_bf16 v[126:129], v[134:137], v[166:169], v[126:129]
	v_mfma_f32_16x16x32_bf16 v[122:125], v[142:145], v[166:169], v[122:125]
	v_mfma_f32_16x16x32_bf16 v[110:113], v[134:137], v[174:177], v[110:113]
	v_mfma_f32_16x16x32_bf16 v[106:109], v[142:145], v[174:177], v[106:109]
	v_mfma_f32_16x16x32_bf16 v[94:97], v[134:137], v[182:185], v[94:97]
	v_mfma_f32_16x16x32_bf16 v[90:93], v[142:145], v[182:185], v[90:93]
	v_mfma_f32_16x16x32_bf16 v[78:81], v[134:137], v[190:193], v[78:81]
	v_mfma_f32_16x16x32_bf16 v[74:77], v[142:145], v[190:193], v[74:77]
	s_setprio 0
	s_setprio 1
	v_mfma_f32_16x16x32_bf16 v[118:121], v[146:149], v[162:165], v[118:121]
	v_mfma_f32_16x16x32_bf16 v[114:117], v[154:157], v[162:165], v[114:117]
	v_mfma_f32_16x16x32_bf16 v[102:105], v[146:149], v[170:173], v[102:105]
	v_mfma_f32_16x16x32_bf16 v[98:101], v[154:157], v[170:173], v[98:101]
	v_mfma_f32_16x16x32_bf16 v[86:89], v[146:149], v[178:181], v[86:89]
	v_mfma_f32_16x16x32_bf16 v[82:85], v[154:157], v[178:181], v[82:85]
	v_mfma_f32_16x16x32_bf16 v[70:73], v[146:149], v[186:189], v[70:73]
	v_mfma_f32_16x16x32_bf16 v[66:69], v[154:157], v[186:189], v[66:69]
	v_mfma_f32_16x16x32_bf16 v[118:121], v[150:153], v[166:169], v[118:121]
	v_mfma_f32_16x16x32_bf16 v[114:117], v[158:161], v[166:169], v[114:117]
	v_mfma_f32_16x16x32_bf16 v[102:105], v[150:153], v[174:177], v[102:105]
	v_mfma_f32_16x16x32_bf16 v[98:101], v[158:161], v[174:177], v[98:101]
	v_mfma_f32_16x16x32_bf16 v[86:89], v[150:153], v[182:185], v[86:89]
	v_mfma_f32_16x16x32_bf16 v[82:85], v[158:161], v[182:185], v[82:85]
	v_mfma_f32_16x16x32_bf16 v[70:73], v[150:153], v[190:193], v[70:73]
	v_mfma_f32_16x16x32_bf16 v[66:69], v[158:161], v[190:193], v[66:69]
	s_setprio 0
	s_barrier
	s_add_i32 s26, s26, s16
	v_lshl_add_u64 v[194:195], s[60:61], 0, v[218:219]
	s_mov_b32 m0, s26
	ds_read_b128 v[162:165], v244 offset:16384
	ds_read_b128 v[166:169], v244 offset:17408
	ds_read_b128 v[170:173], v244 offset:18432
	ds_read_b128 v[174:177], v244 offset:19456
	ds_read_b128 v[178:181], v244 offset:20480
	ds_read_b128 v[182:185], v244 offset:21504
	ds_read_b128 v[186:189], v244 offset:22528
	ds_read_b128 v[190:193], v244 offset:23552
	global_load_lds_dwordx4 v[194:195], off
	s_add_i32 m0, s26, 0x2000
	v_lshl_add_u64 v[196:197], s[60:61], 0, v[214:215]
	s_add_u32 s60, s60, s96
	s_addc_u32 s61, s61, 0
	s_add_i32 s26, s51, s16
	global_load_lds_dwordx4 v[196:197], off
	v_lshl_add_u64 v[198:199], s[60:61], 0, v[218:219]
	s_mov_b32 m0, s26
	v_lshl_add_u64 v[200:201], s[60:61], 0, v[214:215]
	global_load_lds_dwordx4 v[198:199], off
	s_add_i32 m0, s26, 0x2000
	v_lshl_add_u64 v[202:203], s[48:49], 0, v[216:217]
	global_load_lds_dwordx4 v[200:201], off
	s_mov_b32 m0, s17
	v_lshl_add_u64 v[204:205], s[48:49], 0, v[212:213]
	global_load_lds_dwordx4 v[202:203], off
	s_mov_b32 m0, s25
	s_nop 0
	global_load_lds_dwordx4 v[204:205], off
	s_waitcnt vmcnt(8)
	s_waitcnt lgkmcnt(0)
	s_barrier
; #define PG8_STAGE(bufoff, gbase, voff) do { _Pragma("unroll") for (int _i = 0; _i < 2; ++_i) \
;         __builtin_amdgcn_global_load_lds((const unsigned*)((const char*)(gbase) + (voff)[_i]), (PG8_LAS unsigned*)(lds + (bufoff) + ldsw + _i * 8192), 16, 0, 0); } while (0)
; #define PG8_LDA(dst, b, h) do { _Pragma("unroll") for (int m = 0; m < 4; ++m) _Pragma("unroll") for (int k = 0; k < 2; ++k) dst[m][k] = *(const PG8_LAS bf16x8*)(lds + PG8_SA(b, h) + aoff + m * 2048 + k * 1024); } while (0)
; #define PG8_LDB(dst, b, h) do { _Pragma("unroll") for (int n = 0; n < 2; ++n) _Pragma("unroll") for (int k = 0; k < 2; ++k) dst[n][k] = *(const PG8_LAS bf16x8*)(lds + PG8_SB(b, h) + boff + n * 2048 + k * 1024); } while (0)
; #define PG8_MMA(ai, bj, At, Bt) do { __builtin_amdgcn_s_setprio(1); _Pragma("unroll") for (int m = 0; m < 4; ++m) _Pragma("unroll") for (int n = 0; n < 2; ++n) _Pragma("unroll") for (int k = 0; k < 2; ++k) \
;         acc[ai][bj][m][n] = __builtin_amdgcn_mfma_f32_16x16x32_bf16(Bt[n][k], At[m][k], acc[ai][bj][m][n], 0, 0, 0); __builtin_amdgcn_s_setprio(0); } while (0)
; #define PG8_WAIT_V(n) asm volatile("s_waitcnt vmcnt(" #n ")" ::: "memory")
; #define PG8_WAIT_L(n) asm volatile("s_waitcnt lgkmcnt(" #n ")" ::: "memory")
; #define PG8_BAR __builtin_amdgcn_s_barrier()
; #define PG8_SCHED __builtin_amdgcn_sched_barrier(0)
; template <class Epi, class Sched, bool ALIGN_EPI = false, bool SP2 = false>
; __device__ __forceinline__ void gemm_phase(PG8_LAS unsigned char* lds, const Gemm g, const Sched& S, const Epi& E, const int tid_in) {
;     ...
;             PG8_WAIT_V(8); PG8_WAIT_L(0); PG8_BAR; PG8_MMA(1, 0, At, B0); PG8_MMA(1, 1, At, B1); PG8_BAR; PG8_SCHED;
;             PG8_LDB(B0, 1, 0); PG8_LDB(B1, 1, 1); PG8_SCHED; PG8_LDA(At, 1, 0); PG8_STAGE(PG8_SA(0, 1), a2 + hstepA, voffA);
;             PG8_WAIT_V(8); PG8_WAIT_L(0); PG8_BAR; PG8_MMA(0, 0, At, B0); PG8_MMA(0, 1, At, B1); PG8_BAR; PG8_SCHED;
	s_setprio 1
	s_waitcnt lgkmcnt(0)
	v_mfma_f32_16x16x32_bf16 v[62:65], v[130:133], v[162:165], v[62:65]
	v_mfma_f32_16x16x32_bf16 v[58:61], v[138:141], v[162:165], v[58:61]
	v_mfma_f32_16x16x32_bf16 v[46:49], v[130:133], v[170:173], v[46:49]
	v_mfma_f32_16x16x32_bf16 v[42:45], v[138:141], v[170:173], v[42:45]
	v_mfma_f32_16x16x32_bf16 v[30:33], v[130:133], v[178:181], v[30:33]
	v_mfma_f32_16x16x32_bf16 v[26:29], v[138:141], v[178:181], v[26:29]
	v_mfma_f32_16x16x32_bf16 v[14:17], v[130:133], v[186:189], v[14:17]
	v_mfma_f32_16x16x32_bf16 v[10:13], v[138:141], v[186:189], v[10:13]
	v_mfma_f32_16x16x32_bf16 v[62:65], v[134:137], v[166:169], v[62:65]
	v_mfma_f32_16x16x32_bf16 v[58:61], v[142:145], v[166:169], v[58:61]
	v_mfma_f32_16x16x32_bf16 v[46:49], v[134:137], v[174:177], v[46:49]
	v_mfma_f32_16x16x32_bf16 v[42:45], v[142:145], v[174:177], v[42:45]
	v_mfma_f32_16x16x32_bf16 v[30:33], v[134:137], v[182:185], v[30:33]
	v_mfma_f32_16x16x32_bf16 v[26:29], v[142:145], v[182:185], v[26:29]
	v_mfma_f32_16x16x32_bf16 v[14:17], v[134:137], v[190:193], v[14:17]
	v_mfma_f32_16x16x32_bf16 v[10:13], v[142:145], v[190:193], v[10:13]
	s_setprio 0
	s_setprio 1
	v_mfma_f32_16x16x32_bf16 v[54:57], v[146:149], v[162:165], v[54:57]
	v_mfma_f32_16x16x32_bf16 v[50:53], v[154:157], v[162:165], v[50:53]
	v_mfma_f32_16x16x32_bf16 v[38:41], v[146:149], v[170:173], v[38:41]
	v_mfma_f32_16x16x32_bf16 v[34:37], v[154:157], v[170:173], v[34:37]
	v_mfma_f32_16x16x32_bf16 v[22:25], v[146:149], v[178:181], v[22:25]
	v_mfma_f32_16x16x32_bf16 v[18:21], v[154:157], v[178:181], v[18:21]
	v_mfma_f32_16x16x32_bf16 v[6:9], v[146:149], v[186:189], v[6:9]
	v_mfma_f32_16x16x32_bf16 v[2:5], v[154:157], v[186:189], v[2:5]
	v_mfma_f32_16x16x32_bf16 v[54:57], v[150:153], v[166:169], v[54:57]
	v_mfma_f32_16x16x32_bf16 v[50:53], v[158:161], v[166:169], v[50:53]
	v_mfma_f32_16x16x32_bf16 v[38:41], v[150:153], v[174:177], v[38:41]
	v_mfma_f32_16x16x32_bf16 v[34:37], v[158:161], v[174:177], v[34:37]
	v_mfma_f32_16x16x32_bf16 v[22:25], v[150:153], v[182:185], v[22:25]
	v_mfma_f32_16x16x32_bf16 v[18:21], v[158:161], v[182:185], v[18:21]
	v_mfma_f32_16x16x32_bf16 v[6:9], v[150:153], v[190:193], v[6:9]
	v_mfma_f32_16x16x32_bf16 v[2:5], v[158:161], v[190:193], v[2:5]
	s_setprio 0
	s_barrier
	s_add_i32 s26, 0, 0x18000
	s_add_i32 s51, 0, 0x1c000
	v_add_u32_e32 v142, s26, v252
	v_add_u32_e32 v158, s51, v252
	ds_read_b128 v[130:133], v142
	ds_read_b128 v[134:137], v142 offset:1024
	ds_read_b128 v[138:141], v142 offset:2048
	ds_read_b128 v[142:145], v142 offset:3072
	ds_read_b128 v[146:149], v158
	ds_read_b128 v[150:153], v158 offset:1024
	ds_read_b128 v[154:157], v158 offset:2048
	ds_read_b128 v[158:161], v158 offset:3072
	s_add_u32 s48, s48, s12
	s_addc_u32 s49, s49, 0
	s_mov_b32 m0, s57
	v_lshl_add_u64 v[224:225], s[48:49], 0, v[216:217]
	ds_read_b128 v[162:165], v244 offset:32768
	ds_read_b128 v[166:169], v244 offset:33792
	ds_read_b128 v[170:173], v244 offset:34816
	ds_read_b128 v[174:177], v244 offset:35840
	ds_read_b128 v[178:181], v244 offset:36864
	ds_read_b128 v[182:185], v244 offset:37888
	ds_read_b128 v[186:189], v244 offset:38912
	ds_read_b128 v[190:193], v244 offset:39936
	global_load_lds_dwordx4 v[224:225], off
	v_lshl_add_u64 v[224:225], s[48:49], 0, v[212:213]
	s_mov_b32 m0, s0
	s_nop 0
	global_load_lds_dwordx4 v[224:225], off
	s_waitcnt vmcnt(8)
	s_waitcnt lgkmcnt(0)
	s_barrier
	s_setprio 1
	s_waitcnt lgkmcnt(0)
	v_mfma_f32_16x16x32_bf16 v[126:129], v[130:133], v[162:165], v[126:129]
	v_mfma_f32_16x16x32_bf16 v[122:125], v[138:141], v[162:165], v[122:125]
	v_mfma_f32_16x16x32_bf16 v[110:113], v[130:133], v[170:173], v[110:113]
	v_mfma_f32_16x16x32_bf16 v[106:109], v[138:141], v[170:173], v[106:109]
	v_mfma_f32_16x16x32_bf16 v[94:97], v[130:133], v[178:181], v[94:97]
	v_mfma_f32_16x16x32_bf16 v[90:93], v[138:141], v[178:181], v[90:93]
	v_mfma_f32_16x16x32_bf16 v[78:81], v[130:133], v[186:189], v[78:81]
	v_mfma_f32_16x16x32_bf16 v[74:77], v[138:141], v[186:189], v[74:77]
	v_mfma_f32_16x16x32_bf16 v[126:129], v[134:137], v[166:169], v[126:129]
	v_mfma_f32_16x16x32_bf16 v[122:125], v[142:145], v[166:169], v[122:125]
	v_mfma_f32_16x16x32_bf16 v[110:113], v[134:137], v[174:177], v[110:113]
	v_mfma_f32_16x16x32_bf16 v[106:109], v[142:145], v[174:177], v[106:109]
	v_mfma_f32_16x16x32_bf16 v[94:97], v[134:137], v[182:185], v[94:97]
	v_mfma_f32_16x16x32_bf16 v[90:93], v[142:145], v[182:185], v[90:93]
	v_mfma_f32_16x16x32_bf16 v[78:81], v[134:137], v[190:193], v[78:81]
	v_mfma_f32_16x16x32_bf16 v[74:77], v[142:145], v[190:193], v[74:77]
	s_setprio 0
	s_setprio 1
	v_mfma_f32_16x16x32_bf16 v[118:121], v[146:149], v[162:165], v[118:121]
	v_mfma_f32_16x16x32_bf16 v[114:117], v[154:157], v[162:165], v[114:117]
	v_mfma_f32_16x16x32_bf16 v[102:105], v[146:149], v[170:173], v[102:105]
	v_mfma_f32_16x16x32_bf16 v[98:101], v[154:157], v[170:173], v[98:101]
	v_mfma_f32_16x16x32_bf16 v[86:89], v[146:149], v[178:181], v[86:89]
	v_mfma_f32_16x16x32_bf16 v[82:85], v[154:157], v[178:181], v[82:85]
	v_mfma_f32_16x16x32_bf16 v[70:73], v[146:149], v[186:189], v[70:73]
	v_mfma_f32_16x16x32_bf16 v[66:69], v[154:157], v[186:189], v[66:69]
	v_mfma_f32_16x16x32_bf16 v[118:121], v[150:153], v[166:169], v[118:121]
	v_mfma_f32_16x16x32_bf16 v[114:117], v[158:161], v[166:169], v[114:117]
	v_mfma_f32_16x16x32_bf16 v[102:105], v[150:153], v[174:177], v[102:105]
	v_mfma_f32_16x16x32_bf16 v[98:101], v[158:161], v[174:177], v[98:101]
	v_mfma_f32_16x16x32_bf16 v[86:89], v[150:153], v[182:185], v[86:89]
	v_mfma_f32_16x16x32_bf16 v[82:85], v[158:161], v[182:185], v[82:85]
	v_mfma_f32_16x16x32_bf16 v[70:73], v[150:153], v[190:193], v[70:73]
	v_mfma_f32_16x16x32_bf16 v[66:69], v[158:161], v[190:193], v[66:69]
	s_setprio 0
	s_barrier
; #define PG8_STAGE(bufoff, gbase, voff) do { _Pragma("unroll") for (int _i = 0; _i < 2; ++_i) \
;         __builtin_amdgcn_global_load_lds((const unsigned*)((const char*)(gbase) + (voff)[_i]), (PG8_LAS unsigned*)(lds + (bufoff) + ldsw + _i * 8192), 16, 0, 0); } while (0)
; #define PG8_LDA(dst, b, h) do { _Pragma("unroll") for (int m = 0; m < 4; ++m) _Pragma("unroll") for (int k = 0; k < 2; ++k) dst[m][k] = *(const PG8_LAS bf16x8*)(lds + PG8_SA(b, h) + aoff + m * 2048 + k * 1024); } while (0)
; #define PG8_MMA(ai, bj, At, Bt) do { __builtin_amdgcn_s_setprio(1); _Pragma("unroll") for (int m = 0; m < 4; ++m) _Pragma("unroll") for (int n = 0; n < 2; ++n) _Pragma("unroll") for (int k = 0; k < 2; ++k) \
;         acc[ai][bj][m][n] = __builtin_amdgcn_mfma_f32_16x16x32_bf16(Bt[n][k], At[m][k], acc[ai][bj][m][n], 0, 0, 0); __builtin_amdgcn_s_setprio(0); } while (0)
; #define PG8_WAIT_V(n) asm volatile("s_waitcnt vmcnt(" #n ")" ::: "memory")
; #define PG8_WAIT_L(n) asm volatile("s_waitcnt lgkmcnt(" #n ")" ::: "memory")
; #define PG8_BAR __builtin_amdgcn_s_barrier()
; #define PG8_SCHED __builtin_amdgcn_sched_barrier(0)
; template <class Epi, class Sched, bool ALIGN_EPI = false, bool SP2 = false>
; __device__ __forceinline__ void gemm_phase(PG8_LAS unsigned char* lds, const Gemm g, const Sched& S, const Epi& E, const int tid_in) {
;     ...
;             const bool last = (t == nt - 2);
;             const char* a1 = cA + (size_t)(t + 1) * kstep;
;             const char* a2 = last ? nA : cA + (size_t)(t + 2) * kstep; const char* b2 = last ? nB : cB + (size_t)(t + 2) * kstep;
;             const char* a3 = a2 + kstep; const char* b3 = b2 + kstep;
;     ...
;             PG8_LDA(At, 1, 1); PG8_STAGE(PG8_SB(1, 0), b3, voffB); PG8_STAGE(PG8_SB(1, 1), b3 + hstep, voffB); PG8_STAGE(PG8_SA(1, 0), a3, voffA);
;             PG8_WAIT_V(8); PG8_WAIT_L(0); PG8_BAR; PG8_MMA(1, 0, At, B0); PG8_MMA(1, 1, At, B1); PG8_BAR; PG8_SCHED;
	s_add_i32 s26, s26, s16
	v_lshl_add_u64 v[194:195], v[194:195], 0, s[20:21]
	s_mov_b32 m0, s26
	ds_read_b128 v[162:165], v244 offset:49152
	ds_read_b128 v[166:169], v244 offset:50176
	ds_read_b128 v[170:173], v244 offset:51200
	ds_read_b128 v[174:177], v244 offset:52224
	ds_read_b128 v[178:181], v244 offset:53248
	ds_read_b128 v[182:185], v244 offset:54272
	ds_read_b128 v[186:189], v244 offset:55296
	ds_read_b128 v[190:193], v244 offset:56320
	global_load_lds_dwordx4 v[194:195], off
	v_lshl_add_u64 v[194:195], v[196:197], 0, s[20:21]
	s_add_i32 m0, s26, 0x2000
	s_add_i32 s26, s51, s16
	global_load_lds_dwordx4 v[194:195], off
	v_lshl_add_u64 v[194:195], v[198:199], 0, s[20:21]
	s_mov_b32 m0, s26
	s_nop 0
	global_load_lds_dwordx4 v[194:195], off
	v_lshl_add_u64 v[194:195], v[200:201], 0, s[20:21]
	s_add_i32 m0, s26, 0x2000
	s_nop 0
	global_load_lds_dwordx4 v[194:195], off
	v_lshl_add_u64 v[194:195], v[202:203], 0, s[20:21]
	s_mov_b32 m0, s1
	s_nop 0
	global_load_lds_dwordx4 v[194:195], off
	v_lshl_add_u64 v[194:195], v[204:205], 0, s[20:21]
	s_mov_b32 m0, s8
	s_nop 0
	global_load_lds_dwordx4 v[194:195], off
	s_add_u32 vcc_lo, vcc_lo, 0x100
	s_addc_u32 vcc_hi, vcc_hi, 0
	s_add_u32 s46, s46, 0x100
	s_addc_u32 s47, s47, 0
	s_mov_b32 s48, s50
	s_add_i32 s50, s48, 2
	s_add_u32 s51, s46, 0x80
	s_addc_u32 s49, s47, 0
	s_add_i32 s26, 0, 0x10000
	s_cmp_eq_u32 s9, s48
	s_cselect_b32 s49, s83, s49
	s_cselect_b32 s48, s82, s51
	s_cselect_b32 s61, s85, vcc_hi
	s_cselect_b32 s60, s84, vcc_lo
	s_add_i32 s51, 0, 0x14000
	s_add_i32 m0, s50, -2
	s_cmp_ge_u32 m0, s27
	s_waitcnt vmcnt(8)
	s_waitcnt lgkmcnt(0)
	s_barrier
	s_setprio 1
	s_waitcnt lgkmcnt(0)
	v_mfma_f32_16x16x32_bf16 v[62:65], v[130:133], v[162:165], v[62:65]
	v_mfma_f32_16x16x32_bf16 v[58:61], v[138:141], v[162:165], v[58:61]
	v_mfma_f32_16x16x32_bf16 v[46:49], v[130:133], v[170:173], v[46:49]
	v_mfma_f32_16x16x32_bf16 v[42:45], v[138:141], v[170:173], v[42:45]
	v_mfma_f32_16x16x32_bf16 v[30:33], v[130:133], v[178:181], v[30:33]
	v_mfma_f32_16x16x32_bf16 v[26:29], v[138:141], v[178:181], v[26:29]
	v_mfma_f32_16x16x32_bf16 v[14:17], v[130:133], v[186:189], v[14:17]
	v_mfma_f32_16x16x32_bf16 v[10:13], v[138:141], v[186:189], v[10:13]
	v_mfma_f32_16x16x32_bf16 v[62:65], v[134:137], v[166:169], v[62:65]
	v_mfma_f32_16x16x32_bf16 v[58:61], v[142:145], v[166:169], v[58:61]
	v_mfma_f32_16x16x32_bf16 v[46:49], v[134:137], v[174:177], v[46:49]
	v_mfma_f32_16x16x32_bf16 v[42:45], v[142:145], v[174:177], v[42:45]
	v_mfma_f32_16x16x32_bf16 v[30:33], v[134:137], v[182:185], v[30:33]
	v_mfma_f32_16x16x32_bf16 v[26:29], v[142:145], v[182:185], v[26:29]
	v_mfma_f32_16x16x32_bf16 v[14:17], v[134:137], v[190:193], v[14:17]
	v_mfma_f32_16x16x32_bf16 v[10:13], v[142:145], v[190:193], v[10:13]
	s_setprio 0
	s_setprio 1
	v_mfma_f32_16x16x32_bf16 v[54:57], v[146:149], v[162:165], v[54:57]
	v_mfma_f32_16x16x32_bf16 v[50:53], v[154:157], v[162:165], v[50:53]
	v_mfma_f32_16x16x32_bf16 v[38:41], v[146:149], v[170:173], v[38:41]
	v_mfma_f32_16x16x32_bf16 v[34:37], v[154:157], v[170:173], v[34:37]
	v_mfma_f32_16x16x32_bf16 v[22:25], v[146:149], v[178:181], v[22:25]
	v_mfma_f32_16x16x32_bf16 v[18:21], v[154:157], v[178:181], v[18:21]
	v_mfma_f32_16x16x32_bf16 v[6:9], v[146:149], v[186:189], v[6:9]
	v_mfma_f32_16x16x32_bf16 v[2:5], v[154:157], v[186:189], v[2:5]
	v_mfma_f32_16x16x32_bf16 v[54:57], v[150:153], v[166:169], v[54:57]
	v_mfma_f32_16x16x32_bf16 v[50:53], v[158:161], v[166:169], v[50:53]
	v_mfma_f32_16x16x32_bf16 v[38:41], v[150:153], v[174:177], v[38:41]
	v_mfma_f32_16x16x32_bf16 v[34:37], v[158:161], v[174:177], v[34:37]
	v_mfma_f32_16x16x32_bf16 v[22:25], v[150:153], v[182:185], v[22:25]
	v_mfma_f32_16x16x32_bf16 v[18:21], v[158:161], v[182:185], v[18:21]
	v_mfma_f32_16x16x32_bf16 v[6:9], v[150:153], v[190:193], v[6:9]
	v_mfma_f32_16x16x32_bf16 v[2:5], v[158:161], v[190:193], v[2:5]
	s_setprio 0
	s_barrier
	s_cbranch_scc0 .LBB0_226
	s_and_b64 vcc, exec, s[76:77]
	s_cbranch_vccz .LBB0_229
	s_barrier
